# G3 mid-K gate loads: per-load 64-bit VALU address adds with vcc pads replaced by scalar base + 32-bit lane offset (saddr form), 32 loads per rescale; on top of single zeroing + full-line stores
# speedup vs baseline: 1.0027x; 1.0001x over previous
.LBB0_1021:
	s_cmp_eq_u32 s0, 0
	s_cselect_b64 s[2:3], -1, 0
	s_and_b32 s28, s0, 6
	s_cmp_lg_u32 s28, 0
	s_cselect_b64 s[28:29], -1, 0
	s_or_b64 s[2:3], s[2:3], s[28:29]
	s_and_b64 vcc, exec, s[2:3]
	s_cbranch_vccnz .LBB0_1023
	v_readfirstlane_b32 s90, v180
	v_readfirstlane_b32 s91, v181
	s_nop 1
	v_subrev_u32_e32 v251, s90, v180
	s_mov_b32 s2, 0xffff0000
	s_add_u32 s88, s90, 0xffee2000
	s_addc_u32 s89, s91, -1
	global_load_dwordx4 v[196:199], v251, s[88:89] nt
	s_add_u32 s88, s90, 0xfffe2000
	s_addc_u32 s89, s91, -1
	global_load_dwordx4 v[202:205], v251, s[88:89] nt
	s_add_u32 s88, s90, 0xffee4000
	s_addc_u32 s89, s91, -1
	global_load_dwordx4 v[206:209], v251, s[88:89] nt
	s_add_u32 s88, s90, 0xfffe4000
	s_addc_u32 s89, s91, -1
	global_load_dwordx4 v[210:213], v251, s[88:89] nt
	s_add_u32 s88, s90, 0xffee6000
	s_addc_u32 s89, s91, -1
	global_load_dwordx4 v[176:179], v251, s[88:89] nt
	s_add_u32 s88, s90, 0xfffe6000
	s_addc_u32 s89, s91, -1
	global_load_dwordx4 v[172:175], v251, s[88:89] nt
	s_add_u32 s88, s90, 0xffee8000
	s_addc_u32 s89, s91, -1
	global_load_dwordx4 v[168:171], v251, s[88:89] nt
	s_add_u32 s88, s90, 0xfffe8000
	s_addc_u32 s89, s91, -1
	global_load_dwordx4 v[164:167], v251, s[88:89] nt
	s_add_u32 s88, s90, 0xffeea000
	s_addc_u32 s89, s91, -1
	global_load_dwordx4 v[160:163], v251, s[88:89] nt
	s_add_u32 s88, s90, 0xfffea000
	s_addc_u32 s89, s91, -1
	global_load_dwordx4 v[156:159], v251, s[88:89] nt
	s_add_u32 s88, s90, 0xffeec000
	s_addc_u32 s89, s91, -1
	global_load_dwordx4 v[152:155], v251, s[88:89] nt
	s_add_u32 s88, s90, 0xfffec000
	s_addc_u32 s89, s91, -1
	global_load_dwordx4 v[148:151], v251, s[88:89] nt
	s_add_u32 s88, s90, 0xffeee000
	s_addc_u32 s89, s91, -1
	global_load_dwordx4 v[144:147], v251, s[88:89] nt
	s_add_u32 s88, s90, 0xfffee000
	s_addc_u32 s89, s91, -1
	global_load_dwordx4 v[140:143], v251, s[88:89] nt
	s_add_u32 s88, s90, 0xffef0000
	s_addc_u32 s89, s91, -1
	global_load_dwordx4 v[136:139], v251, s[88:89] nt
	s_nop 0
	s_add_u32 s88, s90, 0xffff0000
	s_addc_u32 s89, s91, -1
	global_load_dwordx4 v[132:135], v251, s[88:89] nt
	s_waitcnt vmcnt(15)
	v_lshlrev_b32_e32 v182, 16, v196
	v_and_b32_e32 v183, 0xffff0000, v196
	v_rcp_f32_e32 v182, v182
	v_rcp_f32_e32 v183, v183
	s_waitcnt vmcnt(14)
	v_lshlrev_b32_e32 v188, 16, v202
	v_and_b32_e32 v189, 0xffff0000, v202
	v_pk_mul_f32 v[182:183], v[182:183], v[188:189]
	v_lshlrev_b32_e32 v188, 16, v197
	v_and_b32_e32 v189, 0xffff0000, v197
	v_rcp_f32_e32 v188, v188
	v_rcp_f32_e32 v189, v189
	v_pk_mul_f32 v[128:129], v[128:129], v[182:183]
	v_lshlrev_b32_e32 v182, 16, v203
	v_and_b32_e32 v183, 0xffff0000, v203
	v_pk_mul_f32 v[182:183], v[188:189], v[182:183]
	v_lshlrev_b32_e32 v188, 16, v198
	v_and_b32_e32 v189, 0xffff0000, v198
	v_rcp_f32_e32 v188, v188
	v_rcp_f32_e32 v189, v189
	v_pk_mul_f32 v[130:131], v[130:131], v[182:183]
	v_lshlrev_b32_e32 v182, 16, v204
	v_and_b32_e32 v183, 0xffff0000, v204
	v_pk_mul_f32 v[182:183], v[188:189], v[182:183]
	v_lshlrev_b32_e32 v188, 16, v199
	v_and_b32_e32 v189, 0xffff0000, v199
	v_rcp_f32_e32 v188, v188
	v_rcp_f32_e32 v189, v189
	v_pk_mul_f32 v[124:125], v[124:125], v[182:183]
	v_lshlrev_b32_e32 v182, 16, v205
	v_and_b32_e32 v183, 0xffff0000, v205
	v_pk_mul_f32 v[182:183], v[188:189], v[182:183]
	s_waitcnt vmcnt(13)
	v_lshlrev_b32_e32 v188, 16, v206
	v_and_b32_e32 v189, 0xffff0000, v206
	v_rcp_f32_e32 v188, v188
	v_rcp_f32_e32 v189, v189
	v_pk_mul_f32 v[126:127], v[126:127], v[182:183]
	s_waitcnt vmcnt(12)
	v_lshlrev_b32_e32 v182, 16, v210
	v_and_b32_e32 v183, 0xffff0000, v210
	v_pk_mul_f32 v[182:183], v[188:189], v[182:183]
	v_lshlrev_b32_e32 v188, 16, v207
	v_and_b32_e32 v189, 0xffff0000, v207
	v_rcp_f32_e32 v188, v188
	v_rcp_f32_e32 v189, v189
	v_pk_mul_f32 v[120:121], v[120:121], v[182:183]
	v_lshlrev_b32_e32 v182, 16, v211
	v_and_b32_e32 v183, 0xffff0000, v211
	v_pk_mul_f32 v[182:183], v[188:189], v[182:183]
	v_lshlrev_b32_e32 v188, 16, v208
	v_and_b32_e32 v189, 0xffff0000, v208
	v_rcp_f32_e32 v188, v188
	v_rcp_f32_e32 v189, v189
	v_pk_mul_f32 v[122:123], v[122:123], v[182:183]
	v_lshlrev_b32_e32 v182, 16, v212
	v_and_b32_e32 v183, 0xffff0000, v212
	v_pk_mul_f32 v[182:183], v[188:189], v[182:183]
	v_lshlrev_b32_e32 v188, 16, v209
	v_and_b32_e32 v189, 0xffff0000, v209
	v_rcp_f32_e32 v188, v188
	v_rcp_f32_e32 v189, v189
	v_pk_mul_f32 v[116:117], v[116:117], v[182:183]
	v_lshlrev_b32_e32 v182, 16, v213
	v_and_b32_e32 v183, 0xffff0000, v213
	v_pk_mul_f32 v[182:183], v[188:189], v[182:183]
	s_waitcnt vmcnt(11)
	v_lshlrev_b32_e32 v188, 16, v176
	v_and_b32_e32 v176, 0xffff0000, v176
	v_pk_mul_f32 v[118:119], v[118:119], v[182:183]
	s_waitcnt vmcnt(10)
	v_lshlrev_b32_e32 v182, 16, v172
	v_and_b32_e32 v183, 0xffff0000, v172
	v_lshlrev_b32_e32 v172, 16, v177
	v_rcp_f32_e32 v189, v176
	v_rcp_f32_e32 v176, v172
	v_and_b32_e32 v172, 0xffff0000, v177
	v_rcp_f32_e32 v177, v172
	v_lshlrev_b32_e32 v172, 16, v173
	v_and_b32_e32 v173, 0xffff0000, v173
	v_rcp_f32_e32 v188, v188
	v_pk_mul_f32 v[172:173], v[176:177], v[172:173]
	v_lshlrev_b32_e32 v176, 16, v178
	v_and_b32_e32 v177, 0xffff0000, v178
	v_rcp_f32_e32 v176, v176
	v_rcp_f32_e32 v177, v177
	v_pk_mul_f32 v[114:115], v[114:115], v[172:173]
	v_lshlrev_b32_e32 v172, 16, v174
	v_and_b32_e32 v173, 0xffff0000, v174
	v_lshlrev_b32_e32 v174, 16, v179
	v_pk_mul_f32 v[172:173], v[176:177], v[172:173]
	v_rcp_f32_e32 v176, v174
	v_and_b32_e32 v174, 0xffff0000, v179
	v_rcp_f32_e32 v177, v174
	v_pk_mul_f32 v[108:109], v[108:109], v[172:173]
	v_lshlrev_b32_e32 v172, 16, v175
	v_and_b32_e32 v173, 0xffff0000, v175
	v_pk_mul_f32 v[172:173], v[176:177], v[172:173]
	s_waitcnt vmcnt(9)
	v_lshlrev_b32_e32 v174, 16, v168
	v_and_b32_e32 v168, 0xffff0000, v168
	v_pk_mul_f32 v[110:111], v[110:111], v[172:173]
	s_waitcnt vmcnt(8)
	v_lshlrev_b32_e32 v172, 16, v164
	v_and_b32_e32 v173, 0xffff0000, v164
	v_lshlrev_b32_e32 v164, 16, v169
	v_rcp_f32_e32 v175, v168
	v_rcp_f32_e32 v168, v164
	v_and_b32_e32 v164, 0xffff0000, v169
	v_rcp_f32_e32 v169, v164
	v_lshlrev_b32_e32 v164, 16, v165
	v_and_b32_e32 v165, 0xffff0000, v165
	v_rcp_f32_e32 v174, v174
	v_pk_mul_f32 v[164:165], v[168:169], v[164:165]
	v_lshlrev_b32_e32 v168, 16, v170
	v_and_b32_e32 v169, 0xffff0000, v170
	v_rcp_f32_e32 v168, v168
	v_rcp_f32_e32 v169, v169
	v_pk_mul_f32 v[106:107], v[106:107], v[164:165]
	v_lshlrev_b32_e32 v164, 16, v166
	v_and_b32_e32 v165, 0xffff0000, v166
	v_lshlrev_b32_e32 v166, 16, v171
	v_pk_mul_f32 v[164:165], v[168:169], v[164:165]
	v_rcp_f32_e32 v168, v166
	v_and_b32_e32 v166, 0xffff0000, v171
	v_rcp_f32_e32 v169, v166
	v_pk_mul_f32 v[100:101], v[100:101], v[164:165]
	v_lshlrev_b32_e32 v164, 16, v167
	v_and_b32_e32 v165, 0xffff0000, v167
	v_pk_mul_f32 v[164:165], v[168:169], v[164:165]
	s_waitcnt vmcnt(7)
	v_lshlrev_b32_e32 v166, 16, v160
	v_and_b32_e32 v160, 0xffff0000, v160
	v_pk_mul_f32 v[102:103], v[102:103], v[164:165]
	s_waitcnt vmcnt(6)
	v_lshlrev_b32_e32 v164, 16, v156
	v_and_b32_e32 v165, 0xffff0000, v156
	v_lshlrev_b32_e32 v156, 16, v161
	v_rcp_f32_e32 v167, v160
	v_rcp_f32_e32 v160, v156
	v_and_b32_e32 v156, 0xffff0000, v161
	v_rcp_f32_e32 v161, v156
	v_lshlrev_b32_e32 v156, 16, v157
	v_and_b32_e32 v157, 0xffff0000, v157
	v_rcp_f32_e32 v166, v166
	v_pk_mul_f32 v[156:157], v[160:161], v[156:157]
	v_lshlrev_b32_e32 v160, 16, v162
	v_and_b32_e32 v161, 0xffff0000, v162
	v_rcp_f32_e32 v160, v160
	v_rcp_f32_e32 v161, v161
	v_pk_mul_f32 v[98:99], v[98:99], v[156:157]
	v_lshlrev_b32_e32 v156, 16, v158
	v_and_b32_e32 v157, 0xffff0000, v158
	v_lshlrev_b32_e32 v158, 16, v163
	v_pk_mul_f32 v[156:157], v[160:161], v[156:157]
	v_rcp_f32_e32 v160, v158
	v_and_b32_e32 v158, 0xffff0000, v163
	v_rcp_f32_e32 v161, v158
	v_pk_mul_f32 v[92:93], v[92:93], v[156:157]
	v_lshlrev_b32_e32 v156, 16, v159
	v_and_b32_e32 v157, 0xffff0000, v159
	v_pk_mul_f32 v[156:157], v[160:161], v[156:157]
	s_waitcnt vmcnt(5)
	v_lshlrev_b32_e32 v158, 16, v152
	v_and_b32_e32 v152, 0xffff0000, v152
	v_pk_mul_f32 v[94:95], v[94:95], v[156:157]
	s_waitcnt vmcnt(4)
	v_lshlrev_b32_e32 v156, 16, v148
	v_and_b32_e32 v157, 0xffff0000, v148
	v_lshlrev_b32_e32 v148, 16, v153
	v_rcp_f32_e32 v159, v152
	v_rcp_f32_e32 v152, v148
	v_and_b32_e32 v148, 0xffff0000, v153
	v_rcp_f32_e32 v153, v148
	v_lshlrev_b32_e32 v148, 16, v149
	v_and_b32_e32 v149, 0xffff0000, v149
	v_rcp_f32_e32 v158, v158
	v_pk_mul_f32 v[148:149], v[152:153], v[148:149]
	v_lshlrev_b32_e32 v152, 16, v154
	v_and_b32_e32 v153, 0xffff0000, v154
	v_rcp_f32_e32 v152, v152
	v_rcp_f32_e32 v153, v153
	v_pk_mul_f32 v[90:91], v[90:91], v[148:149]
	v_lshlrev_b32_e32 v148, 16, v150
	v_and_b32_e32 v149, 0xffff0000, v150
	v_lshlrev_b32_e32 v150, 16, v155
	v_pk_mul_f32 v[148:149], v[152:153], v[148:149]
	v_rcp_f32_e32 v152, v150
	v_and_b32_e32 v150, 0xffff0000, v155
	v_rcp_f32_e32 v153, v150
	v_pk_mul_f32 v[84:85], v[84:85], v[148:149]
	v_lshlrev_b32_e32 v148, 16, v151
	v_and_b32_e32 v149, 0xffff0000, v151
	v_pk_mul_f32 v[148:149], v[152:153], v[148:149]
	s_waitcnt vmcnt(3)
	v_lshlrev_b32_e32 v150, 16, v144
	v_and_b32_e32 v144, 0xffff0000, v144
	v_pk_mul_f32 v[86:87], v[86:87], v[148:149]
	s_waitcnt vmcnt(2)
	v_lshlrev_b32_e32 v148, 16, v140
	v_and_b32_e32 v149, 0xffff0000, v140
	v_lshlrev_b32_e32 v140, 16, v145
	v_rcp_f32_e32 v151, v144
	v_rcp_f32_e32 v144, v140
	v_and_b32_e32 v140, 0xffff0000, v145
	v_rcp_f32_e32 v145, v140
	v_lshlrev_b32_e32 v140, 16, v141
	v_and_b32_e32 v141, 0xffff0000, v141
	v_rcp_f32_e32 v150, v150
	v_pk_mul_f32 v[140:141], v[144:145], v[140:141]
	v_lshlrev_b32_e32 v144, 16, v146
	v_and_b32_e32 v145, 0xffff0000, v146
	v_rcp_f32_e32 v144, v144
	v_rcp_f32_e32 v145, v145
	v_pk_mul_f32 v[82:83], v[82:83], v[140:141]
	v_lshlrev_b32_e32 v140, 16, v142
	v_and_b32_e32 v141, 0xffff0000, v142
	v_lshlrev_b32_e32 v142, 16, v147
	v_pk_mul_f32 v[140:141], v[144:145], v[140:141]
	v_rcp_f32_e32 v144, v142
	v_and_b32_e32 v142, 0xffff0000, v147
	v_rcp_f32_e32 v145, v142
	v_pk_mul_f32 v[76:77], v[76:77], v[140:141]
	v_lshlrev_b32_e32 v140, 16, v143
	v_and_b32_e32 v141, 0xffff0000, v143
	v_pk_mul_f32 v[140:141], v[144:145], v[140:141]
	s_waitcnt vmcnt(1)
	v_lshlrev_b32_e32 v142, 16, v136
	v_and_b32_e32 v136, 0xffff0000, v136
	v_pk_mul_f32 v[78:79], v[78:79], v[140:141]
	s_waitcnt vmcnt(0)
	v_lshlrev_b32_e32 v140, 16, v132
	v_and_b32_e32 v141, 0xffff0000, v132
	v_lshlrev_b32_e32 v132, 16, v137
	v_rcp_f32_e32 v143, v136
	v_rcp_f32_e32 v136, v132
	v_and_b32_e32 v132, 0xffff0000, v137
	v_rcp_f32_e32 v137, v132
	v_lshlrev_b32_e32 v132, 16, v133
	v_and_b32_e32 v133, 0xffff0000, v133
	v_rcp_f32_e32 v142, v142
	v_pk_mul_f32 v[132:133], v[136:137], v[132:133]
	v_lshlrev_b32_e32 v136, 16, v138
	v_and_b32_e32 v137, 0xffff0000, v138
	v_rcp_f32_e32 v136, v136
	v_rcp_f32_e32 v137, v137
	v_pk_mul_f32 v[74:75], v[74:75], v[132:133]
	v_lshlrev_b32_e32 v132, 16, v134
	v_and_b32_e32 v133, 0xffff0000, v134
	v_lshlrev_b32_e32 v134, 16, v139
	v_pk_mul_f32 v[132:133], v[136:137], v[132:133]
	v_rcp_f32_e32 v136, v134
	v_and_b32_e32 v134, 0xffff0000, v139
	v_rcp_f32_e32 v137, v134
	v_pk_mul_f32 v[68:69], v[68:69], v[132:133]
	v_lshlrev_b32_e32 v132, 16, v135
	v_and_b32_e32 v133, 0xffff0000, v135
	v_pk_mul_f32 v[182:183], v[188:189], v[182:183]
	v_pk_mul_f32 v[172:173], v[174:175], v[172:173]
	v_pk_mul_f32 v[164:165], v[166:167], v[164:165]
	v_pk_mul_f32 v[156:157], v[158:159], v[156:157]
	v_pk_mul_f32 v[148:149], v[150:151], v[148:149]
	v_pk_mul_f32 v[140:141], v[142:143], v[140:141]
	v_pk_mul_f32 v[132:133], v[136:137], v[132:133]
	v_pk_mul_f32 v[112:113], v[112:113], v[182:183]
	v_pk_mul_f32 v[104:105], v[104:105], v[172:173]
	v_pk_mul_f32 v[96:97], v[96:97], v[164:165]
	v_pk_mul_f32 v[88:89], v[88:89], v[156:157]
	v_pk_mul_f32 v[80:81], v[80:81], v[148:149]
	v_pk_mul_f32 v[72:73], v[72:73], v[140:141]
	v_pk_mul_f32 v[70:71], v[70:71], v[132:133]
	s_mov_b32 s2, 0xffef2000
	s_mov_b32 s2, 0xffff2000
	s_mov_b32 s2, 0xffef4000
	s_add_u32 s88, s90, 0xffef2000
	s_addc_u32 s89, s91, -1
	global_load_dwordx4 v[172:175], v251, s[88:89] nt
	s_add_u32 s88, s90, 0xffff2000
	s_addc_u32 s89, s91, -1
	global_load_dwordx4 v[176:179], v251, s[88:89] nt
	s_mov_b32 s2, 0xffff4000
	s_mov_b32 s2, 0xffef6000
	s_add_u32 s88, s90, 0xffef4000
	s_addc_u32 s89, s91, -1
	global_load_dwordx4 v[196:199], v251, s[88:89] nt
	s_add_u32 s88, s90, 0xffff4000
	s_addc_u32 s89, s91, -1
	global_load_dwordx4 v[202:205], v251, s[88:89] nt
	s_mov_b32 s2, 0xffff6000
	s_mov_b32 s2, 0xffef8000
	s_add_u32 s88, s90, 0xffef6000
	s_addc_u32 s89, s91, -1
	global_load_dwordx4 v[206:209], v251, s[88:89] nt
	s_add_u32 s88, s90, 0xffff6000
	s_addc_u32 s89, s91, -1
	global_load_dwordx4 v[210:213], v251, s[88:89] nt
	s_movk_i32 s2, 0x8000
	s_mov_b32 s2, 0xffefa000
	s_add_u32 s88, s90, 0xffef8000
	s_addc_u32 s89, s91, -1
	global_load_dwordx4 v[168:171], v251, s[88:89] nt
	s_add_u32 s88, s90, 0xffff8000
	s_addc_u32 s89, s91, -1
	global_load_dwordx4 v[164:167], v251, s[88:89] nt
	s_movk_i32 s2, 0xa000
	s_mov_b32 s2, 0xffefc000
	s_add_u32 s88, s90, 0xffefa000
	s_addc_u32 s89, s91, -1
	global_load_dwordx4 v[160:163], v251, s[88:89] nt
	s_add_u32 s88, s90, 0xffffa000
	s_addc_u32 s89, s91, -1
	global_load_dwordx4 v[156:159], v251, s[88:89] nt
	s_movk_i32 s2, 0xc000
	s_mov_b32 s2, 0xffefe000
	s_add_u32 s88, s90, 0xffefc000
	s_addc_u32 s89, s91, -1
	global_load_dwordx4 v[152:155], v251, s[88:89] nt
	s_add_u32 s88, s90, 0xffffc000
	s_addc_u32 s89, s91, -1
	global_load_dwordx4 v[148:151], v251, s[88:89] nt
	s_movk_i32 s2, 0xe000
	s_mov_b32 s2, 0xfff00000
	s_add_u32 s88, s90, 0xffefe000
	s_addc_u32 s89, s91, -1
	global_load_dwordx4 v[144:147], v251, s[88:89] nt
	s_add_u32 s88, s90, 0xffffe000
	s_addc_u32 s89, s91, -1
	global_load_dwordx4 v[140:143], v251, s[88:89] nt
	s_add_u32 s88, s90, 0xfff00000
	s_addc_u32 s89, s91, -1
	global_load_dwordx4 v[136:139], v251, s[88:89] nt
	s_nop 0
	global_load_dwordx4 v[132:135], v251, s[90:91] nt
	s_waitcnt vmcnt(15)
	v_lshlrev_b32_e32 v182, 16, v172
	v_and_b32_e32 v172, 0xffff0000, v172
	v_rcp_f32_e32 v183, v172
	v_lshlrev_b32_e32 v172, 16, v173
	v_and_b32_e32 v173, 0xffff0000, v173
	v_rcp_f32_e32 v172, v172
	v_rcp_f32_e32 v173, v173
	s_waitcnt vmcnt(14)
	v_lshlrev_b32_e32 v188, 16, v176
	v_and_b32_e32 v189, 0xffff0000, v176
	v_lshlrev_b32_e32 v176, 16, v177
	v_and_b32_e32 v177, 0xffff0000, v177
	v_pk_mul_f32 v[172:173], v[172:173], v[176:177]
	v_lshlrev_b32_e32 v176, 16, v174
	v_and_b32_e32 v174, 0xffff0000, v174
	v_rcp_f32_e32 v176, v176
	v_rcp_f32_e32 v177, v174
	v_lshlrev_b32_e32 v174, 16, v175
	v_and_b32_e32 v175, 0xffff0000, v175
	v_rcp_f32_e32 v174, v174
	v_rcp_f32_e32 v175, v175
	v_pk_mul_f32 v[66:67], v[66:67], v[172:173]
	v_lshlrev_b32_e32 v172, 16, v178
	v_and_b32_e32 v173, 0xffff0000, v178
	v_pk_mul_f32 v[172:173], v[176:177], v[172:173]
	v_rcp_f32_e32 v182, v182
	v_pk_mul_f32 v[60:61], v[60:61], v[172:173]
	v_lshlrev_b32_e32 v172, 16, v179
	v_and_b32_e32 v173, 0xffff0000, v179
	v_pk_mul_f32 v[172:173], v[174:175], v[172:173]
	s_waitcnt vmcnt(13)
	v_lshlrev_b32_e32 v174, 16, v196
	v_and_b32_e32 v175, 0xffff0000, v196
	v_rcp_f32_e32 v174, v174
	v_rcp_f32_e32 v175, v175
	v_pk_mul_f32 v[62:63], v[62:63], v[172:173]
	s_waitcnt vmcnt(12)
	v_lshlrev_b32_e32 v172, 16, v202
	v_and_b32_e32 v173, 0xffff0000, v202
	v_pk_mul_f32 v[172:173], v[174:175], v[172:173]
	v_lshlrev_b32_e32 v174, 16, v197
	v_and_b32_e32 v175, 0xffff0000, v197
	v_rcp_f32_e32 v174, v174
	v_rcp_f32_e32 v175, v175
	v_pk_mul_f32 v[56:57], v[56:57], v[172:173]
	v_lshlrev_b32_e32 v172, 16, v203
	v_and_b32_e32 v173, 0xffff0000, v203
	v_pk_mul_f32 v[172:173], v[174:175], v[172:173]
	v_lshlrev_b32_e32 v174, 16, v198
	v_and_b32_e32 v175, 0xffff0000, v198
	v_rcp_f32_e32 v174, v174
	v_rcp_f32_e32 v175, v175
	v_pk_mul_f32 v[58:59], v[58:59], v[172:173]
	v_lshlrev_b32_e32 v172, 16, v204
	v_and_b32_e32 v173, 0xffff0000, v204
	v_pk_mul_f32 v[172:173], v[174:175], v[172:173]
	v_lshlrev_b32_e32 v174, 16, v199
	v_and_b32_e32 v175, 0xffff0000, v199
	v_rcp_f32_e32 v174, v174
	v_rcp_f32_e32 v175, v175
	v_pk_mul_f32 v[52:53], v[52:53], v[172:173]
	v_lshlrev_b32_e32 v172, 16, v205
	v_and_b32_e32 v173, 0xffff0000, v205
	v_pk_mul_f32 v[172:173], v[174:175], v[172:173]
	s_waitcnt vmcnt(11)
	v_lshlrev_b32_e32 v174, 16, v206
	v_and_b32_e32 v175, 0xffff0000, v206
	v_rcp_f32_e32 v174, v174
	v_rcp_f32_e32 v175, v175
	v_pk_mul_f32 v[54:55], v[54:55], v[172:173]
	s_waitcnt vmcnt(10)
	v_lshlrev_b32_e32 v172, 16, v210
	v_and_b32_e32 v173, 0xffff0000, v210
	v_pk_mul_f32 v[172:173], v[174:175], v[172:173]
	v_lshlrev_b32_e32 v174, 16, v207
	v_and_b32_e32 v175, 0xffff0000, v207
	v_rcp_f32_e32 v174, v174
	v_rcp_f32_e32 v175, v175
	v_pk_mul_f32 v[48:49], v[48:49], v[172:173]
	v_lshlrev_b32_e32 v172, 16, v211
	v_and_b32_e32 v173, 0xffff0000, v211
	v_pk_mul_f32 v[172:173], v[174:175], v[172:173]
	v_lshlrev_b32_e32 v174, 16, v208
	v_and_b32_e32 v175, 0xffff0000, v208
	v_rcp_f32_e32 v174, v174
	v_rcp_f32_e32 v175, v175
	v_pk_mul_f32 v[50:51], v[50:51], v[172:173]
	v_lshlrev_b32_e32 v172, 16, v212
	v_and_b32_e32 v173, 0xffff0000, v212
	v_pk_mul_f32 v[172:173], v[174:175], v[172:173]
	v_lshlrev_b32_e32 v174, 16, v209
	v_and_b32_e32 v175, 0xffff0000, v209
	v_rcp_f32_e32 v174, v174
	v_rcp_f32_e32 v175, v175
	v_pk_mul_f32 v[44:45], v[44:45], v[172:173]
	v_lshlrev_b32_e32 v172, 16, v213
	v_and_b32_e32 v173, 0xffff0000, v213
	v_pk_mul_f32 v[172:173], v[174:175], v[172:173]
	s_waitcnt vmcnt(9)
	v_lshlrev_b32_e32 v174, 16, v168
	v_and_b32_e32 v168, 0xffff0000, v168
	v_pk_mul_f32 v[46:47], v[46:47], v[172:173]
	s_waitcnt vmcnt(8)
	v_lshlrev_b32_e32 v172, 16, v164
	v_and_b32_e32 v173, 0xffff0000, v164
	v_lshlrev_b32_e32 v164, 16, v169
	v_rcp_f32_e32 v175, v168
	v_rcp_f32_e32 v168, v164
	v_and_b32_e32 v164, 0xffff0000, v169
	v_rcp_f32_e32 v169, v164
	v_lshlrev_b32_e32 v164, 16, v165
	v_and_b32_e32 v165, 0xffff0000, v165
	v_rcp_f32_e32 v174, v174
	v_pk_mul_f32 v[164:165], v[168:169], v[164:165]
	v_lshlrev_b32_e32 v168, 16, v170
	v_and_b32_e32 v169, 0xffff0000, v170
	v_rcp_f32_e32 v168, v168
	v_rcp_f32_e32 v169, v169
	v_pk_mul_f32 v[42:43], v[42:43], v[164:165]
	v_lshlrev_b32_e32 v164, 16, v166
	v_and_b32_e32 v165, 0xffff0000, v166
	v_lshlrev_b32_e32 v166, 16, v171
	v_pk_mul_f32 v[164:165], v[168:169], v[164:165]
	v_rcp_f32_e32 v168, v166
	v_and_b32_e32 v166, 0xffff0000, v171
	v_rcp_f32_e32 v169, v166
	v_pk_mul_f32 v[36:37], v[36:37], v[164:165]
	v_lshlrev_b32_e32 v164, 16, v167
	v_and_b32_e32 v165, 0xffff0000, v167
	v_pk_mul_f32 v[164:165], v[168:169], v[164:165]
	s_waitcnt vmcnt(7)
	v_lshlrev_b32_e32 v166, 16, v160
	v_and_b32_e32 v160, 0xffff0000, v160
	v_pk_mul_f32 v[38:39], v[38:39], v[164:165]
	s_waitcnt vmcnt(6)
	v_lshlrev_b32_e32 v164, 16, v156
	v_and_b32_e32 v165, 0xffff0000, v156
	v_lshlrev_b32_e32 v156, 16, v161
	v_rcp_f32_e32 v167, v160
	v_rcp_f32_e32 v160, v156
	v_and_b32_e32 v156, 0xffff0000, v161
	v_rcp_f32_e32 v161, v156
	v_lshlrev_b32_e32 v156, 16, v157
	v_and_b32_e32 v157, 0xffff0000, v157
	v_rcp_f32_e32 v166, v166
	v_pk_mul_f32 v[156:157], v[160:161], v[156:157]
	v_lshlrev_b32_e32 v160, 16, v162
	v_and_b32_e32 v161, 0xffff0000, v162
	v_rcp_f32_e32 v160, v160
	v_rcp_f32_e32 v161, v161
	v_pk_mul_f32 v[34:35], v[34:35], v[156:157]
	v_lshlrev_b32_e32 v156, 16, v158
	v_and_b32_e32 v157, 0xffff0000, v158
	v_lshlrev_b32_e32 v158, 16, v163
	v_pk_mul_f32 v[156:157], v[160:161], v[156:157]
	v_rcp_f32_e32 v160, v158
	v_and_b32_e32 v158, 0xffff0000, v163
	v_rcp_f32_e32 v161, v158
	v_pk_mul_f32 v[28:29], v[28:29], v[156:157]
	v_lshlrev_b32_e32 v156, 16, v159
	v_and_b32_e32 v157, 0xffff0000, v159
	v_pk_mul_f32 v[156:157], v[160:161], v[156:157]
	s_waitcnt vmcnt(5)
	v_lshlrev_b32_e32 v158, 16, v152
	v_and_b32_e32 v152, 0xffff0000, v152
	v_pk_mul_f32 v[30:31], v[30:31], v[156:157]
	s_waitcnt vmcnt(4)
	v_lshlrev_b32_e32 v156, 16, v148
	v_and_b32_e32 v157, 0xffff0000, v148
	v_lshlrev_b32_e32 v148, 16, v153
	v_rcp_f32_e32 v159, v152
	v_rcp_f32_e32 v152, v148
	v_and_b32_e32 v148, 0xffff0000, v153
	v_rcp_f32_e32 v153, v148
	v_lshlrev_b32_e32 v148, 16, v149
	v_and_b32_e32 v149, 0xffff0000, v149
	v_rcp_f32_e32 v158, v158
	v_pk_mul_f32 v[148:149], v[152:153], v[148:149]
	v_lshlrev_b32_e32 v152, 16, v154
	v_and_b32_e32 v153, 0xffff0000, v154
	v_rcp_f32_e32 v152, v152
	v_rcp_f32_e32 v153, v153
	v_pk_mul_f32 v[26:27], v[26:27], v[148:149]
	v_lshlrev_b32_e32 v148, 16, v150
	v_and_b32_e32 v149, 0xffff0000, v150
	v_lshlrev_b32_e32 v150, 16, v155
	v_pk_mul_f32 v[148:149], v[152:153], v[148:149]
	v_rcp_f32_e32 v152, v150
	v_and_b32_e32 v150, 0xffff0000, v155
	v_rcp_f32_e32 v153, v150
	v_pk_mul_f32 v[20:21], v[20:21], v[148:149]
	v_lshlrev_b32_e32 v148, 16, v151
	v_and_b32_e32 v149, 0xffff0000, v151
	v_pk_mul_f32 v[148:149], v[152:153], v[148:149]
	s_waitcnt vmcnt(3)
	v_lshlrev_b32_e32 v150, 16, v144
	v_and_b32_e32 v144, 0xffff0000, v144
	v_pk_mul_f32 v[22:23], v[22:23], v[148:149]
	s_waitcnt vmcnt(2)
	v_lshlrev_b32_e32 v148, 16, v140
	v_and_b32_e32 v149, 0xffff0000, v140
	v_lshlrev_b32_e32 v140, 16, v145
	v_rcp_f32_e32 v151, v144
	v_rcp_f32_e32 v144, v140
	v_and_b32_e32 v140, 0xffff0000, v145
	v_rcp_f32_e32 v145, v140
	v_lshlrev_b32_e32 v140, 16, v141
	v_and_b32_e32 v141, 0xffff0000, v141
	v_rcp_f32_e32 v150, v150
	v_pk_mul_f32 v[140:141], v[144:145], v[140:141]
	v_lshlrev_b32_e32 v144, 16, v146
	v_and_b32_e32 v145, 0xffff0000, v146
	v_rcp_f32_e32 v144, v144
	v_rcp_f32_e32 v145, v145
	v_pk_mul_f32 v[18:19], v[18:19], v[140:141]
	v_lshlrev_b32_e32 v140, 16, v142
	v_and_b32_e32 v141, 0xffff0000, v142
	v_lshlrev_b32_e32 v142, 16, v147
	v_pk_mul_f32 v[140:141], v[144:145], v[140:141]
	v_rcp_f32_e32 v144, v142
	v_and_b32_e32 v142, 0xffff0000, v147
	v_rcp_f32_e32 v145, v142
	v_pk_mul_f32 v[12:13], v[12:13], v[140:141]
	v_lshlrev_b32_e32 v140, 16, v143
	v_and_b32_e32 v141, 0xffff0000, v143
	v_pk_mul_f32 v[140:141], v[144:145], v[140:141]
	s_waitcnt vmcnt(1)
	v_lshlrev_b32_e32 v142, 16, v136
	v_and_b32_e32 v136, 0xffff0000, v136
	v_pk_mul_f32 v[14:15], v[14:15], v[140:141]
	s_waitcnt vmcnt(0)
	v_lshlrev_b32_e32 v140, 16, v132
	v_and_b32_e32 v141, 0xffff0000, v132
	v_lshlrev_b32_e32 v132, 16, v137
	v_rcp_f32_e32 v143, v136
	v_rcp_f32_e32 v136, v132
	v_and_b32_e32 v132, 0xffff0000, v137
	v_rcp_f32_e32 v137, v132
	v_lshlrev_b32_e32 v132, 16, v133
	v_and_b32_e32 v133, 0xffff0000, v133
	v_rcp_f32_e32 v142, v142
	v_pk_mul_f32 v[132:133], v[136:137], v[132:133]
	v_lshlrev_b32_e32 v136, 16, v138
	v_and_b32_e32 v137, 0xffff0000, v138
	v_rcp_f32_e32 v136, v136
	v_rcp_f32_e32 v137, v137
	v_pk_mul_f32 v[10:11], v[10:11], v[132:133]
	v_lshlrev_b32_e32 v132, 16, v134
	v_and_b32_e32 v133, 0xffff0000, v134
	v_lshlrev_b32_e32 v134, 16, v139
	v_pk_mul_f32 v[132:133], v[136:137], v[132:133]
	v_rcp_f32_e32 v136, v134
	v_and_b32_e32 v134, 0xffff0000, v139
	v_rcp_f32_e32 v137, v134
	v_pk_mul_f32 v[4:5], v[4:5], v[132:133]
	v_lshlrev_b32_e32 v132, 16, v135
	v_and_b32_e32 v133, 0xffff0000, v135
	v_pk_mul_f32 v[182:183], v[182:183], v[188:189]
	v_pk_mul_f32 v[172:173], v[174:175], v[172:173]
	v_pk_mul_f32 v[164:165], v[166:167], v[164:165]
	v_pk_mul_f32 v[156:157], v[158:159], v[156:157]
	v_pk_mul_f32 v[148:149], v[150:151], v[148:149]
	v_pk_mul_f32 v[140:141], v[142:143], v[140:141]
	v_pk_mul_f32 v[132:133], v[136:137], v[132:133]
	v_pk_mul_f32 v[64:65], v[64:65], v[182:183]
	v_pk_mul_f32 v[40:41], v[40:41], v[172:173]
	v_pk_mul_f32 v[32:33], v[32:33], v[164:165]
	v_pk_mul_f32 v[24:25], v[24:25], v[156:157]
	v_pk_mul_f32 v[16:17], v[16:17], v[148:149]
	v_pk_mul_f32 v[8:9], v[8:9], v[140:141]
	v_pk_mul_f32 v[6:7], v[6:7], v[132:133]
